# GLA scan cache policy: non-temporal hint also on the output-tile flush stores
# baseline (speedup 1.0000x reference)
; __device__ __forceinline__ int crow(int r, int hi) { return (r & 3) + 8 * (r >> 2) + 4 * hi; }
; __device__ __forceinline__ int v_st(int k, int c) { const int kk = (k & ~0xC) | ((k & 4) << 1) | ((k & 8) >> 1); return ((kk >> 3) * 4 + (c >> 5)) * 512 + ((kk & 7) * 32 + (c & 31)) * 2; }
; #define OPAQUE_TID(name) int name = MK_TID; asm volatile("" : "+v"(name))
; __device__ __forceinline__ void scan_unit(const int unit, const Args& a, unsigned char* lds, const int mk_wid) {
;     ...
;         GLA_FLUSH();
;         { OPAQUE_TID(t_);
; #pragma unroll
;           for (int p = 0; p < 2; ++p) { const int i_ = p * 32 + (t_ >> 4), c_ = (t_ & 15) * 8; *(bf16x8*)(qe + i_ * QP + c_) = qraw[p]; *(bf16x8*)(ke + i_ * QP + c_) = kraw[p]; }
; #pragma unroll
;           for (int p = 0; p < 4; ++p) { const int i_ = p * 16 + (t_ >> 5), c8 = t_ & 31; *(bf16x8*)(lds + L_V + (c8 >> 4) * 16384 + v_st(i_, (c8 & 15) * 8)) = vraw[p]; }
;           if (t_ < 128) *(bf16x8*)(lds + L_LR + (t_ >> 1) * 32 + (t_ & 1) * 16) = lraw; }
;         __syncthreads();
;         { OPAQUE_TID(t_); const int lane = t_ & 63, r32 = lane & 31, hi = lane >> 5; const int tt = wid >> 2, ct = wid & 3;
;           const bf16x8 af = *(const bf16x8*)(lds + L_LR + (tt * 32 + r32) * 32 + hi * 16);
;           const f32x16 z = __builtin_amdgcn_mfma_f32_32x32x16_bf16(af, upf, f32x16{}, 0, 0, 0);
;           float* lw = las + (tt * 32 + 4 * hi) * 128 + ct * 32 + r32;
; #pragma unroll
;           for (int r = 0; r < 16; ++r) { const float zz = z[r] + biasc;
;               lw[crow(r, 0) * 128] = (fminf(zz, 0.f) - __builtin_amdgcn_logf(1.f + __builtin_amdgcn_exp2f(-1.4426950408889634f * fabsf(zz))) * 0.6931471805599453f) * (1.f / 16.f); } }
;         __syncthreads();
;         { OPAQUE_TID(t_); const int c = t_ & 127, g = t_ >> 7;
;           float bl[16]; float run = 0.f;
;           { const float* lp = las + (g * 16) * 128 + c;
; #pragma unroll
;             for (int ii = 0; ii < 16; ++ii) { run += lp[ii * 128]; bl[ii] = run; } }
;           gs[g * 128 + c] = run;
;           __syncthreads();
;           const float g0 = gs[c], g1 = gs[128 + c], g2 = gs[256 + c], g3 = gs[384 + c];
.Lscan_noflush:
	v_mbcnt_lo_u32_b32 v64, -1, 0
	v_mbcnt_hi_u32_b32 v64, -1, v64
	s_nop 0
	v_add_u32_e32 v64, s72, v64
	s_nop 0
	v_and_b32_e32 v68, 31, v64
	v_bfe_u32 v69, v64, 5, 1
	v_lshlrev_b32_e32 v69, 11, v69
	v_lshlrev_b32_e32 v68, 2, v68
	v_add3_u32 v80, s45, v69, v68
	v_mfma_f32_32x32x16_bf16 v[64:79], v[96:99], v[108:111], 0
	s_mov_b32 s96, 1.0
	s_mov_b32 s97, 0xbf317218
	s_mov_b32 s98, 0x3db8aa3b
	s_nop 11
	v_pk_add_f32 v[64:65], v[64:65], v[156:157] op_sel_hi:[1,0]
	v_pk_add_f32 v[66:67], v[66:67], v[156:157] op_sel_hi:[1,0]
	v_pk_add_f32 v[68:69], v[68:69], v[156:157] op_sel_hi:[1,0]
	v_pk_add_f32 v[70:71], v[70:71], v[156:157] op_sel_hi:[1,0]
	v_mul_f32_e64 v82, |v64|, s54
	v_mul_f32_e64 v83, |v65|, s54
	v_mul_f32_e64 v84, |v66|, s54
	v_mul_f32_e64 v85, |v67|, s54
	v_mul_f32_e64 v86, |v68|, s54
	v_mul_f32_e64 v87, |v69|, s54
	v_mul_f32_e64 v88, |v70|, s54
	v_mul_f32_e64 v89, |v71|, s54
	v_exp_f32_e32 v82, v82
	v_exp_f32_e32 v83, v83
	v_exp_f32_e32 v84, v84
	v_exp_f32_e32 v85, v85
	v_exp_f32_e32 v86, v86
	v_exp_f32_e32 v87, v87
	v_exp_f32_e32 v88, v88
	v_exp_f32_e32 v89, v89
	v_pk_add_f32 v[82:83], v[82:83], s[96:97] op_sel_hi:[1,0]
	v_pk_add_f32 v[84:85], v[84:85], s[96:97] op_sel_hi:[1,0]
	v_pk_add_f32 v[86:87], v[86:87], s[96:97] op_sel_hi:[1,0]
	v_pk_add_f32 v[88:89], v[88:89], s[96:97] op_sel_hi:[1,0]
	v_log_f32_e32 v82, v82
	v_log_f32_e32 v83, v83
	v_log_f32_e32 v84, v84
	v_log_f32_e32 v85, v85
	v_log_f32_e32 v86, v86
	v_log_f32_e32 v87, v87
	v_log_f32_e32 v88, v88
	v_log_f32_e32 v89, v89
	v_min_f32_e32 v64, 0, v64
	v_min_f32_e32 v65, 0, v65
	v_min_f32_e32 v66, 0, v66
	v_min_f32_e32 v67, 0, v67
	v_min_f32_e32 v68, 0, v68
	v_min_f32_e32 v69, 0, v69
	v_min_f32_e32 v70, 0, v70
	v_min_f32_e32 v71, 0, v71
	v_pk_fma_f32 v[64:65], v[82:83], s[96:97], v[64:65] op_sel:[0,1,0] op_sel_hi:[1,1,1]
	v_pk_fma_f32 v[66:67], v[84:85], s[96:97], v[66:67] op_sel:[0,1,0] op_sel_hi:[1,1,1]
	v_pk_fma_f32 v[68:69], v[86:87], s[96:97], v[68:69] op_sel:[0,1,0] op_sel_hi:[1,1,1]
	v_pk_fma_f32 v[70:71], v[88:89], s[96:97], v[70:71] op_sel:[0,1,0] op_sel_hi:[1,1,1]
	v_pk_mul_f32 v[64:65], v[64:65], s[98:99] op_sel_hi:[1,0]
	v_pk_mul_f32 v[66:67], v[66:67], s[98:99] op_sel_hi:[1,0]
	v_pk_mul_f32 v[68:69], v[68:69], s[98:99] op_sel_hi:[1,0]
	v_pk_mul_f32 v[70:71], v[70:71], s[98:99] op_sel_hi:[1,0]
	ds_write2st64_b32 v80, v64, v65 offset1:2
	ds_write2st64_b32 v80, v66, v67 offset0:4 offset1:6
	ds_write2st64_b32 v80, v68, v69 offset0:16 offset1:18
	ds_write2st64_b32 v80, v70, v71 offset0:20 offset1:22
	v_pk_add_f32 v[72:73], v[72:73], v[156:157] op_sel_hi:[1,0]
	v_pk_add_f32 v[74:75], v[74:75], v[156:157] op_sel_hi:[1,0]
	v_pk_add_f32 v[76:77], v[76:77], v[156:157] op_sel_hi:[1,0]
	v_pk_add_f32 v[78:79], v[78:79], v[156:157] op_sel_hi:[1,0]
	v_mul_f32_e64 v82, |v72|, s54
	v_mul_f32_e64 v83, |v73|, s54
	v_mul_f32_e64 v84, |v74|, s54
	v_mul_f32_e64 v85, |v75|, s54
	v_mul_f32_e64 v86, |v76|, s54
	v_mul_f32_e64 v87, |v77|, s54
	v_mul_f32_e64 v88, |v78|, s54
	v_mul_f32_e64 v89, |v79|, s54
	v_exp_f32_e32 v82, v82
	v_exp_f32_e32 v83, v83
	v_exp_f32_e32 v84, v84
	v_exp_f32_e32 v85, v85
	v_exp_f32_e32 v86, v86
	v_exp_f32_e32 v87, v87
	v_exp_f32_e32 v88, v88
	v_exp_f32_e32 v89, v89
	v_pk_add_f32 v[82:83], v[82:83], s[96:97] op_sel_hi:[1,0]
	v_pk_add_f32 v[84:85], v[84:85], s[96:97] op_sel_hi:[1,0]
	v_pk_add_f32 v[86:87], v[86:87], s[96:97] op_sel_hi:[1,0]
	v_pk_add_f32 v[88:89], v[88:89], s[96:97] op_sel_hi:[1,0]
	v_log_f32_e32 v82, v82
	v_log_f32_e32 v83, v83
	v_log_f32_e32 v84, v84
	v_log_f32_e32 v85, v85
	v_log_f32_e32 v86, v86
	v_log_f32_e32 v87, v87
	v_log_f32_e32 v88, v88
	v_log_f32_e32 v89, v89
	v_min_f32_e32 v72, 0, v72
	v_min_f32_e32 v73, 0, v73
	v_min_f32_e32 v74, 0, v74
	v_min_f32_e32 v75, 0, v75
	v_min_f32_e32 v76, 0, v76
	v_min_f32_e32 v77, 0, v77
	v_min_f32_e32 v78, 0, v78
	v_min_f32_e32 v79, 0, v79
	v_pk_fma_f32 v[72:73], v[82:83], s[96:97], v[72:73] op_sel:[0,1,0] op_sel_hi:[1,1,1]
	v_pk_fma_f32 v[74:75], v[84:85], s[96:97], v[74:75] op_sel:[0,1,0] op_sel_hi:[1,1,1]
	v_pk_fma_f32 v[76:77], v[86:87], s[96:97], v[76:77] op_sel:[0,1,0] op_sel_hi:[1,1,1]
	v_pk_fma_f32 v[78:79], v[88:89], s[96:97], v[78:79] op_sel:[0,1,0] op_sel_hi:[1,1,1]
	v_pk_mul_f32 v[72:73], v[72:73], s[98:99] op_sel_hi:[1,0]
	v_pk_mul_f32 v[74:75], v[74:75], s[98:99] op_sel_hi:[1,0]
	v_pk_mul_f32 v[76:77], v[76:77], s[98:99] op_sel_hi:[1,0]
	v_pk_mul_f32 v[78:79], v[78:79], s[98:99] op_sel_hi:[1,0]
	ds_write2st64_b32 v80, v72, v73 offset0:32 offset1:34
	ds_write2st64_b32 v80, v74, v75 offset0:36 offset1:38
	ds_write2st64_b32 v80, v76, v77 offset0:48 offset1:50
	ds_write2st64_b32 v80, v78, v79 offset0:52 offset1:54
	v_pk_add_f32 v[82:83], v[64:65], v[66:67]
	v_pk_add_f32 v[84:85], v[68:69], v[70:71]
	v_pk_add_f32 v[86:87], v[72:73], v[74:75]
	v_pk_add_f32 v[88:89], v[76:77], v[78:79]
	v_add_f32_e32 v82, v82, v83
	v_add_f32_e32 v84, v84, v85
	v_add_f32_e32 v86, v86, v87
	v_add_f32_e32 v88, v88, v89
	ds_write2st64_b32 v169, v82, v84 offset1:4
	ds_write2st64_b32 v169, v86, v88 offset0:8 offset1:12
	s_waitcnt lgkmcnt(0)
	s_barrier
	v_mbcnt_lo_u32_b32 v64, -1, 0
	v_mbcnt_hi_u32_b32 v64, -1, v64
	s_lshl_b32 s96, s70, 12
	s_add_i32 s96, s96, s9
	v_lshl_add_u32 v65, v64, 3, s96
	v_lshlrev_b32_e32 v67, 3, v64
	v_add_u32_e32 v67, 0x20000, v67
	ds_read2st64_b64 v[186:189], v67 offset1:1
	ds_read2st64_b64 v[190:193], v67 offset0:2 offset1:3
	ds_read2st64_b64 v[194:197], v67 offset0:4 offset1:5
	ds_read2st64_b64 v[198:201], v67 offset0:6 offset1:7
	ds_read2st64_b64 v[202:205], v67 offset0:8 offset1:9
	ds_read2st64_b64 v[206:209], v67 offset0:10 offset1:11
	ds_read2st64_b64 v[210:213], v67 offset0:12 offset1:13
	ds_read2st64_b64 v[214:217], v67 offset0:14 offset1:15
	ds_read2st64_b64 v[170:173], v65 offset1:1
	ds_read2st64_b64 v[174:177], v65 offset0:2 offset1:3
	ds_read2st64_b64 v[178:181], v65 offset0:4 offset1:5
	ds_read2st64_b64 v[182:185], v65 offset0:6 offset1:7
	s_cmp_lt_i32 s34, 0
	s_cbranch_scc1 .Lscan_nofl2
	global_store_dwordx4 v252, v[112:115], s[26:27] nt
	global_store_dwordx4 v165, v[116:119], s[26:27] nt
	global_store_dwordx4 v166, v[120:123], s[26:27] nt
	global_store_dwordx4 v167, v[124:127], s[26:27] nt
